# P2/P4 epilogues: transposed bf16 short stores issued as global_store_short instead of flat_store_short
# baseline (speedup 1.0000x reference)
; DI unsigned short f2bf(float x) { return (unsigned short)(pk2(x, 0.f) & 0xffffu); }
; DI uint4 pk8(f32x4 a, f32x4 b) { return make_uint4(pk2(a[0], a[1]), pk2(a[2], a[3]), pk2(b[0], b[1]), pk2(b[2], b[3])); }
;     DI void operator()(const f32x4 (&acc)[2][2][4][2], const pg8::Unit& u, int wr, int wc, int fr, int fq) const {
;     ...
;         const int t0 = u.pm * 256 + wr * 64 + fr;
;         if (pn < 4) {
; #pragma unroll
;             for (int i = 0; i < 16; ++i) {
;                 const int ai = TILE_AI(i), m = TILE_M(i), bj = TILE_BJ(i);
;                 const int t = t0 + ai * 128 + m * 16, col = colb + bj * 128;
;                 const f32x4 v0 = acc[ai][bj][m][0] + bia[bj][0], v1 = acc[ai][bj][m][1] + bia[bj][1];
;                 *(uint4*)(xm + (size_t)t * 1024 + col) = pk8(v0, v1);
;                 const int b = t >> 13, sidx = t & 8191;
;                 bf16_t* tp = xmT + ((((size_t)(b * 4 + (col >> 8)) * 128 + (sidx >> 6)) * 256 + (col & 255)) * 64) + (sidx & 63);
; #pragma unroll
;                 for (int r = 0; r < 4; ++r) { *tp = f2bf(v0[r]); tp += 64; asm volatile("" : "+v"(tp)); }
; #pragma unroll
;                 for (int r = 0; r < 4; ++r) { *tp = f2bf(v1[r]); tp += 64; asm volatile("" : "+v"(tp)); }
;             }
.LBB0_301:
	v_ashrrev_i32_e32 v163, 31, v162
	v_readlane_b32 s18, v254, 56
	v_lshlrev_b64 v[166:167], 11, v[162:163]
	v_readlane_b32 s19, v254, 57
	v_cvt_pk_bf16_f32 v178, v140, v141
	v_cvt_pk_bf16_f32 v179, v142, v143
	v_lshl_add_u64 v[168:169], s[18:19], 0, v[166:167]
	v_lshlrev_b64 v[166:167], 1, v[164:165]
	v_cvt_pk_bf16_f32 v180, v136, v137
	v_cvt_pk_bf16_f32 v181, v138, v139
	v_lshl_add_u64 v[168:169], v[168:169], 0, v[166:167]
	v_ashrrev_i32_e32 v152, 11, v162
	global_store_dwordx4 v[168:169], v[178:181], off
	v_ashrrev_i32_e32 v163, 8, v164
	v_and_b32_e32 v165, 0xf8, v177
	v_and_b32_e32 v180, -4, v152
	v_add_u32_e32 v178, v163, v180
	v_ashrrev_i32_e32 v179, 31, v178
	v_lshlrev_b32_e32 v152, 2, v162
	v_lshlrev_b64 v[178:179], 15, v[178:179]
	v_and_b32_e32 v181, 0x7f00, v152
	v_or3_b32 v178, v178, v181, v165
	v_lshlrev_b64 v[178:179], 7, v[178:179]
	v_and_b32_e32 v152, 63, v176
	v_lshl_add_u64 v[178:179], s[92:93], 0, v[178:179]
	v_lshlrev_b32_e32 v152, 1, v152
	v_lshl_add_u64 v[176:177], v[178:179], 0, v[152:153]
	v_cvt_pk_bf16_f32 v140, v140, s0
	global_store_short v[176:177], v140, off
	v_lshl_add_u64 v[176:177], v[176:177], 0, s[10:11]
	v_cvt_pk_bf16_f32 v140, v141, s0
	global_store_short v[176:177], v140, off
	v_lshl_add_u64 v[140:141], v[176:177], 0, s[10:11]
	v_cvt_pk_bf16_f32 v142, v142, s0
	global_store_short v[140:141], v142, off
	v_lshl_add_u64 v[140:141], v[140:141], 0, s[10:11]
	v_cvt_pk_bf16_f32 v142, v143, s0
	global_store_short v[140:141], v142, off
	v_lshl_add_u64 v[140:141], v[140:141], 0, s[10:11]
	v_cvt_pk_bf16_f32 v136, v136, s0
	global_store_short v[140:141], v136, off
	v_lshl_add_u64 v[140:141], v[140:141], 0, s[10:11]
	v_cvt_pk_bf16_f32 v136, v137, s0
	global_store_short v[140:141], v136, off
	v_lshl_add_u64 v[136:137], v[140:141], 0, s[10:11]
	v_cvt_pk_bf16_f32 v138, v138, s0
	global_store_short v[136:137], v138, off
	v_lshl_add_u64 v[136:137], v[136:137], 0, s[10:11]
	v_cvt_pk_bf16_f32 v138, v139, s0
	global_store_short v[136:137], v138, off
	v_lshl_add_u64 v[136:137], v[136:137], 0, s[10:11]
	v_pk_add_f32 v[134:135], v[134:135], v[98:99]
	v_pk_add_f32 v[132:133], v[132:133], v[96:97]
	v_pk_add_f32 v[136:137], v[130:131], v[94:95]
	v_pk_add_f32 v[138:139], v[128:129], v[92:93]
	v_add_u32_e32 v140, 0x80, v164
	v_cvt_pk_bf16_f32 v128, v132, v133
	v_cvt_pk_bf16_f32 v129, v134, v135
	v_cvt_pk_bf16_f32 v130, v138, v139
	v_cvt_pk_bf16_f32 v131, v136, v137
	global_store_dwordx4 v[168:169], v[128:131], off offset:256
	v_cvt_pk_bf16_f32 v132, v132, s0
	v_pk_add_f32 v[126:127], v[126:127], v[118:119]
	v_ashrrev_i32_e32 v128, 8, v140
	v_add_u32_e32 v130, v128, v180
	v_ashrrev_i32_e32 v131, 31, v130
	v_lshlrev_b64 v[130:131], 15, v[130:131]
	v_and_b32_e32 v129, 0xf8, v140
	v_or3_b32 v130, v130, v181, v129
	v_lshlrev_b64 v[130:131], 7, v[130:131]
	v_lshl_add_u64 v[130:131], s[92:93], 0, v[130:131]
	v_lshl_add_u64 v[130:131], v[130:131], 0, v[152:153]
	global_store_short v[130:131], v132, off
	v_lshl_add_u64 v[130:131], v[130:131], 0, s[10:11]
	v_cvt_pk_bf16_f32 v132, v133, s0
	global_store_short v[130:131], v132, off
	v_lshl_add_u64 v[130:131], v[130:131], 0, s[10:11]
	v_cvt_pk_bf16_f32 v132, v134, s0
	global_store_short v[130:131], v132, off
	v_lshl_add_u64 v[130:131], v[130:131], 0, s[10:11]
	v_cvt_pk_bf16_f32 v132, v135, s0
	global_store_short v[130:131], v132, off
	v_lshl_add_u64 v[130:131], v[130:131], 0, s[10:11]
	v_cvt_pk_bf16_f32 v132, v138, s0
	global_store_short v[130:131], v132, off
	v_lshl_add_u64 v[130:131], v[130:131], 0, s[10:11]
	v_cvt_pk_bf16_f32 v132, v139, s0
	global_store_short v[130:131], v132, off
	v_lshl_add_u64 v[130:131], v[130:131], 0, s[10:11]
	v_cvt_pk_bf16_f32 v132, v136, s0
	global_store_short v[130:131], v132, off
	v_lshl_add_u64 v[130:131], v[130:131], 0, s[10:11]
	v_cvt_pk_bf16_f32 v132, v137, s0
	global_store_short v[130:131], v132, off
	v_lshl_add_u64 v[130:131], v[130:131], 0, s[10:11]
	v_pk_add_f32 v[124:125], v[124:125], v[116:117]
	v_add_u32_e32 v130, 16, v162
	v_ashrrev_i32_e32 v131, 31, v130
	v_lshlrev_b64 v[136:137], 11, v[130:131]
	v_pk_add_f32 v[132:133], v[122:123], v[114:115]
	v_pk_add_f32 v[134:135], v[120:121], v[112:113]
	v_lshl_add_u64 v[136:137], s[18:19], 0, v[136:137]
	v_cvt_pk_bf16_f32 v120, v124, v125
	v_cvt_pk_bf16_f32 v121, v126, v127
	v_cvt_pk_bf16_f32 v122, v134, v135
	v_cvt_pk_bf16_f32 v123, v132, v133
	v_lshl_add_u64 v[136:137], v[136:137], 0, v[166:167]
	global_store_dwordx4 v[136:137], v[120:123], off
	v_cvt_pk_bf16_f32 v124, v124, s0
	v_pk_add_f32 v[110:111], v[110:111], v[98:99]
	v_ashrrev_i32_e32 v120, 11, v130
	v_and_b32_e32 v131, -4, v120
	v_add_u32_e32 v120, v163, v131
	v_ashrrev_i32_e32 v121, 31, v120
	v_lshlrev_b32_e32 v122, 2, v130
	v_lshlrev_b64 v[120:121], 15, v[120:121]
	v_and_b32_e32 v138, 0x7f00, v122
	v_or3_b32 v120, v120, v138, v165
	v_lshlrev_b64 v[120:121], 7, v[120:121]
	v_and_b32_e32 v122, 63, v130
	v_lshl_add_u64 v[120:121], s[92:93], 0, v[120:121]
	v_lshlrev_b32_e32 v122, 1, v122
	v_mov_b32_e32 v123, v153
	v_lshl_add_u64 v[120:121], v[120:121], 0, v[122:123]
	global_store_short v[120:121], v124, off
	v_lshl_add_u64 v[120:121], v[120:121], 0, s[10:11]
	v_cvt_pk_bf16_f32 v124, v125, s0
	global_store_short v[120:121], v124, off
	v_lshl_add_u64 v[120:121], v[120:121], 0, s[10:11]
	v_cvt_pk_bf16_f32 v124, v126, s0
	global_store_short v[120:121], v124, off
	v_lshl_add_u64 v[120:121], v[120:121], 0, s[10:11]
	v_cvt_pk_bf16_f32 v124, v127, s0
	global_store_short v[120:121], v124, off
	v_lshl_add_u64 v[120:121], v[120:121], 0, s[10:11]
	v_cvt_pk_bf16_f32 v124, v134, s0
	global_store_short v[120:121], v124, off
	v_lshl_add_u64 v[120:121], v[120:121], 0, s[10:11]
; DI unsigned short f2bf(float x) { return (unsigned short)(pk2(x, 0.f) & 0xffffu); }
; DI uint4 pk8(f32x4 a, f32x4 b) { return make_uint4(pk2(a[0], a[1]), pk2(a[2], a[3]), pk2(b[0], b[1]), pk2(b[2], b[3])); }
;     DI void operator()(const f32x4 (&acc)[2][2][4][2], const pg8::Unit& u, int wr, int wc, int fr, int fq) const {
;     ...
;         const int t0 = u.pm * 256 + wr * 64 + fr;
;         if (pn < 4) {
; #pragma unroll
;             for (int i = 0; i < 16; ++i) {
;                 const int ai = TILE_AI(i), m = TILE_M(i), bj = TILE_BJ(i);
;                 const int t = t0 + ai * 128 + m * 16, col = colb + bj * 128;
;                 const f32x4 v0 = acc[ai][bj][m][0] + bia[bj][0], v1 = acc[ai][bj][m][1] + bia[bj][1];
;                 *(uint4*)(xm + (size_t)t * 1024 + col) = pk8(v0, v1);
;                 const int b = t >> 13, sidx = t & 8191;
;                 bf16_t* tp = xmT + ((((size_t)(b * 4 + (col >> 8)) * 128 + (sidx >> 6)) * 256 + (col & 255)) * 64) + (sidx & 63);
; #pragma unroll
;                 for (int r = 0; r < 4; ++r) { *tp = f2bf(v0[r]); tp += 64; asm volatile("" : "+v"(tp)); }
; #pragma unroll
;                 for (int r = 0; r < 4; ++r) { *tp = f2bf(v1[r]); tp += 64; asm volatile("" : "+v"(tp)); }
;             }
	v_cvt_pk_bf16_f32 v124, v135, s0
	global_store_short v[120:121], v124, off
	v_lshl_add_u64 v[120:121], v[120:121], 0, s[10:11]
	v_cvt_pk_bf16_f32 v124, v132, s0
	global_store_short v[120:121], v124, off
	v_lshl_add_u64 v[120:121], v[120:121], 0, s[10:11]
	v_cvt_pk_bf16_f32 v124, v133, s0
	global_store_short v[120:121], v124, off
	v_lshl_add_u64 v[120:121], v[120:121], 0, s[10:11]
	v_pk_add_f32 v[108:109], v[108:109], v[96:97]
	v_pk_add_f32 v[120:121], v[106:107], v[94:95]
	v_pk_add_f32 v[124:125], v[104:105], v[92:93]
	v_cvt_pk_bf16_f32 v104, v108, v109
	v_cvt_pk_bf16_f32 v105, v110, v111
	v_cvt_pk_bf16_f32 v106, v124, v125
	v_cvt_pk_bf16_f32 v107, v120, v121
	global_store_dwordx4 v[136:137], v[104:107], off offset:256
	v_pk_add_f32 v[102:103], v[102:103], v[118:119]
	v_pk_add_f32 v[100:101], v[100:101], v[116:117]
	v_add_u32_e32 v104, v128, v131
	v_ashrrev_i32_e32 v105, 31, v104
	v_lshlrev_b64 v[104:105], 15, v[104:105]
	v_or3_b32 v104, v104, v138, v129
	v_lshlrev_b64 v[104:105], 7, v[104:105]
	v_lshl_add_u64 v[104:105], s[92:93], 0, v[104:105]
	v_lshl_add_u64 v[104:105], v[104:105], 0, v[122:123]
	v_cvt_pk_bf16_f32 v106, v108, s0
	global_store_short v[104:105], v106, off
	v_lshl_add_u64 v[104:105], v[104:105], 0, s[10:11]
	v_cvt_pk_bf16_f32 v106, v109, s0
	global_store_short v[104:105], v106, off
	v_lshl_add_u64 v[104:105], v[104:105], 0, s[10:11]
	v_cvt_pk_bf16_f32 v106, v110, s0
	global_store_short v[104:105], v106, off
	v_lshl_add_u64 v[104:105], v[104:105], 0, s[10:11]
	v_cvt_pk_bf16_f32 v106, v111, s0
	global_store_short v[104:105], v106, off
	v_lshl_add_u64 v[104:105], v[104:105], 0, s[10:11]
	v_cvt_pk_bf16_f32 v106, v124, s0
	global_store_short v[104:105], v106, off
	v_lshl_add_u64 v[104:105], v[104:105], 0, s[10:11]
	v_cvt_pk_bf16_f32 v106, v125, s0
	global_store_short v[104:105], v106, off
	v_lshl_add_u64 v[104:105], v[104:105], 0, s[10:11]
	v_cvt_pk_bf16_f32 v106, v120, s0
	global_store_short v[104:105], v106, off
	v_lshl_add_u64 v[104:105], v[104:105], 0, s[10:11]
	v_cvt_pk_bf16_f32 v106, v121, s0
	global_store_short v[104:105], v106, off
	v_lshl_add_u64 v[104:105], v[104:105], 0, s[10:11]
	v_pk_add_f32 v[106:107], v[90:91], v[114:115]
	v_add_u32_e32 v104, 32, v162
	v_ashrrev_i32_e32 v105, 31, v104
	v_lshlrev_b64 v[110:111], 11, v[104:105]
	v_pk_add_f32 v[108:109], v[88:89], v[112:113]
	v_lshl_add_u64 v[110:111], s[18:19], 0, v[110:111]
	v_cvt_pk_bf16_f32 v88, v100, v101
	v_cvt_pk_bf16_f32 v89, v102, v103
	v_cvt_pk_bf16_f32 v90, v108, v109
	v_cvt_pk_bf16_f32 v91, v106, v107
	v_lshl_add_u64 v[110:111], v[110:111], 0, v[166:167]
	global_store_dwordx4 v[110:111], v[88:91], off
	v_cvt_pk_bf16_f32 v100, v100, s0
	v_pk_add_f32 v[86:87], v[86:87], v[98:99]
	v_ashrrev_i32_e32 v88, 11, v104
	v_and_b32_e32 v105, -4, v88
	v_add_u32_e32 v88, v163, v105
	v_ashrrev_i32_e32 v89, 31, v88
	v_lshlrev_b32_e32 v90, 2, v104
	v_lshlrev_b64 v[88:89], 15, v[88:89]
	v_and_b32_e32 v120, 0x7f00, v90
	v_or3_b32 v88, v88, v120, v165
	v_lshlrev_b64 v[88:89], 7, v[88:89]
	v_and_b32_e32 v90, 63, v104
	v_lshl_add_u64 v[88:89], s[92:93], 0, v[88:89]
	v_lshlrev_b32_e32 v90, 1, v90
	v_mov_b32_e32 v91, v153
	v_lshl_add_u64 v[88:89], v[88:89], 0, v[90:91]
	global_store_short v[88:89], v100, off
	v_lshl_add_u64 v[88:89], v[88:89], 0, s[10:11]
	v_cvt_pk_bf16_f32 v100, v101, s0
	global_store_short v[88:89], v100, off
	v_lshl_add_u64 v[88:89], v[88:89], 0, s[10:11]
	v_cvt_pk_bf16_f32 v100, v102, s0
	global_store_short v[88:89], v100, off
	v_lshl_add_u64 v[88:89], v[88:89], 0, s[10:11]
	v_cvt_pk_bf16_f32 v100, v103, s0
	global_store_short v[88:89], v100, off
	v_lshl_add_u64 v[88:89], v[88:89], 0, s[10:11]
	v_cvt_pk_bf16_f32 v100, v108, s0
	global_store_short v[88:89], v100, off
	v_lshl_add_u64 v[88:89], v[88:89], 0, s[10:11]
	v_cvt_pk_bf16_f32 v100, v109, s0
	global_store_short v[88:89], v100, off
	v_lshl_add_u64 v[88:89], v[88:89], 0, s[10:11]
	v_cvt_pk_bf16_f32 v100, v106, s0
	global_store_short v[88:89], v100, off
	v_lshl_add_u64 v[88:89], v[88:89], 0, s[10:11]
	v_cvt_pk_bf16_f32 v100, v107, s0
	global_store_short v[88:89], v100, off
	v_lshl_add_u64 v[88:89], v[88:89], 0, s[10:11]
	v_pk_add_f32 v[84:85], v[84:85], v[96:97]
	v_pk_add_f32 v[88:89], v[82:83], v[94:95]
	v_pk_add_f32 v[100:101], v[80:81], v[92:93]
	v_cvt_pk_bf16_f32 v80, v84, v85
	v_cvt_pk_bf16_f32 v81, v86, v87
	v_cvt_pk_bf16_f32 v82, v100, v101
	v_cvt_pk_bf16_f32 v83, v88, v89
	global_store_dwordx4 v[110:111], v[80:83], off offset:256
	v_pk_add_f32 v[78:79], v[78:79], v[118:119]
	v_pk_add_f32 v[76:77], v[76:77], v[116:117]
	v_add_u32_e32 v80, v128, v105
	v_ashrrev_i32_e32 v81, 31, v80
	v_lshlrev_b64 v[80:81], 15, v[80:81]
	v_or3_b32 v80, v80, v120, v129
	v_lshlrev_b64 v[80:81], 7, v[80:81]
	v_lshl_add_u64 v[80:81], s[92:93], 0, v[80:81]
	v_lshl_add_u64 v[80:81], v[80:81], 0, v[90:91]
	v_cvt_pk_bf16_f32 v82, v84, s0
	global_store_short v[80:81], v82, off
	v_lshl_add_u64 v[80:81], v[80:81], 0, s[10:11]
	v_cvt_pk_bf16_f32 v82, v85, s0
	global_store_short v[80:81], v82, off
	v_lshl_add_u64 v[80:81], v[80:81], 0, s[10:11]
	v_cvt_pk_bf16_f32 v82, v86, s0
	global_store_short v[80:81], v82, off
	v_lshl_add_u64 v[80:81], v[80:81], 0, s[10:11]
	v_cvt_pk_bf16_f32 v82, v87, s0
	global_store_short v[80:81], v82, off
	v_lshl_add_u64 v[80:81], v[80:81], 0, s[10:11]
	v_cvt_pk_bf16_f32 v82, v100, s0
	global_store_short v[80:81], v82, off
	v_lshl_add_u64 v[80:81], v[80:81], 0, s[10:11]
	v_cvt_pk_bf16_f32 v82, v101, s0
	global_store_short v[80:81], v82, off
	v_lshl_add_u64 v[80:81], v[80:81], 0, s[10:11]
	v_cvt_pk_bf16_f32 v82, v88, s0
	global_store_short v[80:81], v82, off
	v_lshl_add_u64 v[80:81], v[80:81], 0, s[10:11]
; DI unsigned short f2bf(float x) { return (unsigned short)(pk2(x, 0.f) & 0xffffu); }
; DI uint4 pk8(f32x4 a, f32x4 b) { return make_uint4(pk2(a[0], a[1]), pk2(a[2], a[3]), pk2(b[0], b[1]), pk2(b[2], b[3])); }
;     DI void operator()(const f32x4 (&acc)[2][2][4][2], const pg8::Unit& u, int wr, int wc, int fr, int fq) const {
;     ...
;         const int t0 = u.pm * 256 + wr * 64 + fr;
;         if (pn < 4) {
; #pragma unroll
;             for (int i = 0; i < 16; ++i) {
;                 const int ai = TILE_AI(i), m = TILE_M(i), bj = TILE_BJ(i);
;                 const int t = t0 + ai * 128 + m * 16, col = colb + bj * 128;
;                 const f32x4 v0 = acc[ai][bj][m][0] + bia[bj][0], v1 = acc[ai][bj][m][1] + bia[bj][1];
;                 *(uint4*)(xm + (size_t)t * 1024 + col) = pk8(v0, v1);
;                 const int b = t >> 13, sidx = t & 8191;
;                 bf16_t* tp = xmT + ((((size_t)(b * 4 + (col >> 8)) * 128 + (sidx >> 6)) * 256 + (col & 255)) * 64) + (sidx & 63);
; #pragma unroll
;                 for (int r = 0; r < 4; ++r) { *tp = f2bf(v0[r]); tp += 64; asm volatile("" : "+v"(tp)); }
; #pragma unroll
;                 for (int r = 0; r < 4; ++r) { *tp = f2bf(v1[r]); tp += 64; asm volatile("" : "+v"(tp)); }
;             }
	v_cvt_pk_bf16_f32 v82, v89, s0
	global_store_short v[80:81], v82, off
	v_lshl_add_u64 v[80:81], v[80:81], 0, s[10:11]
	v_pk_add_f32 v[82:83], v[74:75], v[114:115]
	v_add_u32_e32 v80, 48, v162
	v_ashrrev_i32_e32 v81, 31, v80
	v_lshlrev_b64 v[86:87], 11, v[80:81]
	v_pk_add_f32 v[84:85], v[72:73], v[112:113]
	v_lshl_add_u64 v[86:87], s[18:19], 0, v[86:87]
	v_cvt_pk_bf16_f32 v72, v76, v77
	v_cvt_pk_bf16_f32 v73, v78, v79
	v_cvt_pk_bf16_f32 v74, v84, v85
	v_cvt_pk_bf16_f32 v75, v82, v83
	v_lshl_add_u64 v[86:87], v[86:87], 0, v[166:167]
	global_store_dwordx4 v[86:87], v[72:75], off
	v_cvt_pk_bf16_f32 v76, v76, s0
	v_pk_add_f32 v[70:71], v[70:71], v[98:99]
	v_ashrrev_i32_e32 v72, 11, v80
	v_and_b32_e32 v81, -4, v72
	v_add_u32_e32 v72, v163, v81
	v_ashrrev_i32_e32 v73, 31, v72
	v_lshlrev_b32_e32 v74, 2, v80
	v_lshlrev_b64 v[72:73], 15, v[72:73]
	v_and_b32_e32 v88, 0x7f00, v74
	v_or3_b32 v72, v72, v88, v165
	v_lshlrev_b64 v[72:73], 7, v[72:73]
	v_and_b32_e32 v74, 63, v80
	v_lshl_add_u64 v[72:73], s[92:93], 0, v[72:73]
	v_lshlrev_b32_e32 v74, 1, v74
	v_mov_b32_e32 v75, v153
	v_lshl_add_u64 v[72:73], v[72:73], 0, v[74:75]
	global_store_short v[72:73], v76, off
	v_lshl_add_u64 v[72:73], v[72:73], 0, s[10:11]
	v_cvt_pk_bf16_f32 v76, v77, s0
	global_store_short v[72:73], v76, off
	v_lshl_add_u64 v[72:73], v[72:73], 0, s[10:11]
	v_cvt_pk_bf16_f32 v76, v78, s0
	global_store_short v[72:73], v76, off
	v_lshl_add_u64 v[72:73], v[72:73], 0, s[10:11]
	v_cvt_pk_bf16_f32 v76, v79, s0
	global_store_short v[72:73], v76, off
	v_lshl_add_u64 v[72:73], v[72:73], 0, s[10:11]
	v_cvt_pk_bf16_f32 v76, v84, s0
	global_store_short v[72:73], v76, off
	v_lshl_add_u64 v[72:73], v[72:73], 0, s[10:11]
	v_cvt_pk_bf16_f32 v76, v85, s0
	global_store_short v[72:73], v76, off
	v_lshl_add_u64 v[72:73], v[72:73], 0, s[10:11]
	v_cvt_pk_bf16_f32 v76, v82, s0
	global_store_short v[72:73], v76, off
	v_lshl_add_u64 v[72:73], v[72:73], 0, s[10:11]
	v_cvt_pk_bf16_f32 v76, v83, s0
	global_store_short v[72:73], v76, off
	v_lshl_add_u64 v[72:73], v[72:73], 0, s[10:11]
	v_pk_add_f32 v[68:69], v[68:69], v[96:97]
	v_pk_add_f32 v[72:73], v[66:67], v[94:95]
	v_pk_add_f32 v[76:77], v[64:65], v[92:93]
	v_cvt_pk_bf16_f32 v64, v68, v69
	v_cvt_pk_bf16_f32 v65, v70, v71
	v_cvt_pk_bf16_f32 v66, v76, v77
	v_cvt_pk_bf16_f32 v67, v72, v73
	global_store_dwordx4 v[86:87], v[64:67], off offset:256
	v_pk_add_f32 v[62:63], v[62:63], v[118:119]
	v_pk_add_f32 v[60:61], v[60:61], v[116:117]
	v_add_u32_e32 v64, v128, v81
	v_ashrrev_i32_e32 v65, 31, v64
	v_lshlrev_b64 v[64:65], 15, v[64:65]
	v_or3_b32 v64, v64, v88, v129
	v_lshlrev_b64 v[64:65], 7, v[64:65]
	v_lshl_add_u64 v[64:65], s[92:93], 0, v[64:65]
	v_lshl_add_u64 v[64:65], v[64:65], 0, v[74:75]
	v_cvt_pk_bf16_f32 v66, v68, s0
	global_store_short v[64:65], v66, off
	v_lshl_add_u64 v[64:65], v[64:65], 0, s[10:11]
	v_cvt_pk_bf16_f32 v66, v69, s0
	global_store_short v[64:65], v66, off
	v_lshl_add_u64 v[64:65], v[64:65], 0, s[10:11]
	v_cvt_pk_bf16_f32 v66, v70, s0
	global_store_short v[64:65], v66, off
	v_lshl_add_u64 v[64:65], v[64:65], 0, s[10:11]
	v_cvt_pk_bf16_f32 v66, v71, s0
	global_store_short v[64:65], v66, off
	v_lshl_add_u64 v[64:65], v[64:65], 0, s[10:11]
	v_cvt_pk_bf16_f32 v66, v76, s0
	global_store_short v[64:65], v66, off
	v_lshl_add_u64 v[64:65], v[64:65], 0, s[10:11]
	v_cvt_pk_bf16_f32 v66, v77, s0
	global_store_short v[64:65], v66, off
	v_lshl_add_u64 v[64:65], v[64:65], 0, s[10:11]
	v_cvt_pk_bf16_f32 v66, v72, s0
	global_store_short v[64:65], v66, off
	v_lshl_add_u64 v[64:65], v[64:65], 0, s[10:11]
	v_cvt_pk_bf16_f32 v66, v73, s0
	global_store_short v[64:65], v66, off
	v_lshl_add_u64 v[64:65], v[64:65], 0, s[10:11]
	v_pk_add_f32 v[66:67], v[58:59], v[114:115]
	v_add_u32_e32 v64, 0x80, v162
	v_ashrrev_i32_e32 v65, 31, v64
	v_lshlrev_b64 v[70:71], 11, v[64:65]
	v_pk_add_f32 v[68:69], v[56:57], v[112:113]
	v_lshl_add_u64 v[70:71], s[18:19], 0, v[70:71]
	v_cvt_pk_bf16_f32 v56, v60, v61
	v_cvt_pk_bf16_f32 v57, v62, v63
	v_cvt_pk_bf16_f32 v58, v68, v69
	v_cvt_pk_bf16_f32 v59, v66, v67
	v_lshl_add_u64 v[70:71], v[70:71], 0, v[166:167]
	global_store_dwordx4 v[70:71], v[56:59], off
	v_pk_add_f32 v[54:55], v[54:55], v[98:99]
	v_pk_add_f32 v[52:53], v[52:53], v[96:97]
	v_ashrrev_i32_e32 v56, 11, v64
	v_and_b32_e32 v65, -4, v56
	v_add_u32_e32 v56, v163, v65
	v_ashrrev_i32_e32 v57, 31, v56
	v_lshlrev_b32_e32 v58, 2, v64
	v_lshlrev_b64 v[56:57], 15, v[56:57]
	v_and_b32_e32 v64, 0x7f00, v58
	v_or3_b32 v56, v56, v64, v165
	v_lshlrev_b64 v[56:57], 7, v[56:57]
	v_lshl_add_u64 v[56:57], s[92:93], 0, v[56:57]
	v_lshl_add_u64 v[56:57], v[56:57], 0, v[152:153]
	v_cvt_pk_bf16_f32 v58, v60, s0
	global_store_short v[56:57], v58, off
	v_lshl_add_u64 v[56:57], v[56:57], 0, s[10:11]
	v_cvt_pk_bf16_f32 v58, v61, s0
	global_store_short v[56:57], v58, off
	v_lshl_add_u64 v[56:57], v[56:57], 0, s[10:11]
	v_cvt_pk_bf16_f32 v58, v62, s0
	global_store_short v[56:57], v58, off
	v_lshl_add_u64 v[56:57], v[56:57], 0, s[10:11]
	v_cvt_pk_bf16_f32 v58, v63, s0
	global_store_short v[56:57], v58, off
	v_lshl_add_u64 v[56:57], v[56:57], 0, s[10:11]
	v_cvt_pk_bf16_f32 v58, v68, s0
	global_store_short v[56:57], v58, off
	v_lshl_add_u64 v[56:57], v[56:57], 0, s[10:11]
	v_cvt_pk_bf16_f32 v58, v69, s0
	global_store_short v[56:57], v58, off
	v_lshl_add_u64 v[56:57], v[56:57], 0, s[10:11]
	v_cvt_pk_bf16_f32 v58, v66, s0
	global_store_short v[56:57], v58, off
	v_lshl_add_u64 v[56:57], v[56:57], 0, s[10:11]
	v_cvt_pk_bf16_f32 v58, v67, s0
	global_store_short v[56:57], v58, off
	v_lshl_add_u64 v[56:57], v[56:57], 0, s[10:11]
	v_pk_add_f32 v[58:59], v[48:49], v[92:93]
	v_pk_add_f32 v[56:57], v[50:51], v[94:95]
; DI unsigned short f2bf(float x) { return (unsigned short)(pk2(x, 0.f) & 0xffffu); }
; DI uint4 pk8(f32x4 a, f32x4 b) { return make_uint4(pk2(a[0], a[1]), pk2(a[2], a[3]), pk2(b[0], b[1]), pk2(b[2], b[3])); }
;     DI void operator()(const f32x4 (&acc)[2][2][4][2], const pg8::Unit& u, int wr, int wc, int fr, int fq) const {
;     ...
;         const int t0 = u.pm * 256 + wr * 64 + fr;
;         if (pn < 4) {
; #pragma unroll
;             for (int i = 0; i < 16; ++i) {
;                 const int ai = TILE_AI(i), m = TILE_M(i), bj = TILE_BJ(i);
;                 const int t = t0 + ai * 128 + m * 16, col = colb + bj * 128;
;                 const f32x4 v0 = acc[ai][bj][m][0] + bia[bj][0], v1 = acc[ai][bj][m][1] + bia[bj][1];
;                 *(uint4*)(xm + (size_t)t * 1024 + col) = pk8(v0, v1);
;                 const int b = t >> 13, sidx = t & 8191;
;                 bf16_t* tp = xmT + ((((size_t)(b * 4 + (col >> 8)) * 128 + (sidx >> 6)) * 256 + (col & 255)) * 64) + (sidx & 63);
; #pragma unroll
;                 for (int r = 0; r < 4; ++r) { *tp = f2bf(v0[r]); tp += 64; asm volatile("" : "+v"(tp)); }
; #pragma unroll
;                 for (int r = 0; r < 4; ++r) { *tp = f2bf(v1[r]); tp += 64; asm volatile("" : "+v"(tp)); }
;             }
	v_cvt_pk_bf16_f32 v48, v52, v53
	v_cvt_pk_bf16_f32 v49, v54, v55
	v_cvt_pk_bf16_f32 v50, v58, v59
	v_cvt_pk_bf16_f32 v51, v56, v57
	global_store_dwordx4 v[70:71], v[48:51], off offset:256
	v_pk_add_f32 v[46:47], v[46:47], v[118:119]
	v_pk_add_f32 v[44:45], v[44:45], v[116:117]
	v_add_u32_e32 v48, v128, v65
	v_ashrrev_i32_e32 v49, 31, v48
	v_lshlrev_b64 v[48:49], 15, v[48:49]
	v_or3_b32 v48, v48, v64, v129
	v_lshlrev_b64 v[48:49], 7, v[48:49]
	v_lshl_add_u64 v[48:49], s[92:93], 0, v[48:49]
	v_lshl_add_u64 v[48:49], v[48:49], 0, v[152:153]
	v_cvt_pk_bf16_f32 v50, v52, s0
	global_store_short v[48:49], v50, off
	v_lshl_add_u64 v[48:49], v[48:49], 0, s[10:11]
	v_cvt_pk_bf16_f32 v50, v53, s0
	global_store_short v[48:49], v50, off
	v_lshl_add_u64 v[48:49], v[48:49], 0, s[10:11]
	v_cvt_pk_bf16_f32 v50, v54, s0
	global_store_short v[48:49], v50, off
	v_lshl_add_u64 v[48:49], v[48:49], 0, s[10:11]
	v_cvt_pk_bf16_f32 v50, v55, s0
	global_store_short v[48:49], v50, off
	v_lshl_add_u64 v[48:49], v[48:49], 0, s[10:11]
	v_cvt_pk_bf16_f32 v50, v58, s0
	global_store_short v[48:49], v50, off
	v_lshl_add_u64 v[48:49], v[48:49], 0, s[10:11]
	v_cvt_pk_bf16_f32 v50, v59, s0
	global_store_short v[48:49], v50, off
	v_lshl_add_u64 v[48:49], v[48:49], 0, s[10:11]
	v_cvt_pk_bf16_f32 v50, v56, s0
	global_store_short v[48:49], v50, off
	v_lshl_add_u64 v[48:49], v[48:49], 0, s[10:11]
	v_cvt_pk_bf16_f32 v50, v57, s0
	global_store_short v[48:49], v50, off
	v_lshl_add_u64 v[48:49], v[48:49], 0, s[10:11]
	v_pk_add_f32 v[50:51], v[42:43], v[114:115]
	v_add_u32_e32 v48, 0x90, v162
	v_ashrrev_i32_e32 v49, 31, v48
	v_lshlrev_b64 v[54:55], 11, v[48:49]
	v_pk_add_f32 v[52:53], v[40:41], v[112:113]
	v_lshl_add_u64 v[54:55], s[18:19], 0, v[54:55]
	v_cvt_pk_bf16_f32 v40, v44, v45
	v_cvt_pk_bf16_f32 v41, v46, v47
	v_cvt_pk_bf16_f32 v42, v52, v53
	v_cvt_pk_bf16_f32 v43, v50, v51
	v_lshl_add_u64 v[54:55], v[54:55], 0, v[166:167]
	global_store_dwordx4 v[54:55], v[40:43], off
	v_pk_add_f32 v[38:39], v[38:39], v[98:99]
	v_pk_add_f32 v[36:37], v[36:37], v[96:97]
	v_ashrrev_i32_e32 v40, 11, v48
	v_and_b32_e32 v49, -4, v40
	v_add_u32_e32 v40, v163, v49
	v_ashrrev_i32_e32 v41, 31, v40
	v_lshlrev_b32_e32 v42, 2, v48
	v_lshlrev_b64 v[40:41], 15, v[40:41]
	v_and_b32_e32 v56, 0x7f00, v42
	v_or3_b32 v40, v40, v56, v165
	v_lshlrev_b64 v[40:41], 7, v[40:41]
	v_and_b32_e32 v42, 63, v48
	v_lshl_add_u64 v[40:41], s[92:93], 0, v[40:41]
	v_lshlrev_b32_e32 v152, 1, v42
	v_lshl_add_u64 v[40:41], v[40:41], 0, v[152:153]
	v_cvt_pk_bf16_f32 v42, v44, s0
	global_store_short v[40:41], v42, off
	v_lshl_add_u64 v[40:41], v[40:41], 0, s[10:11]
	v_cvt_pk_bf16_f32 v42, v45, s0
	global_store_short v[40:41], v42, off
	v_lshl_add_u64 v[40:41], v[40:41], 0, s[10:11]
	v_cvt_pk_bf16_f32 v42, v46, s0
	global_store_short v[40:41], v42, off
	v_lshl_add_u64 v[40:41], v[40:41], 0, s[10:11]
	v_cvt_pk_bf16_f32 v42, v47, s0
	global_store_short v[40:41], v42, off
	v_lshl_add_u64 v[40:41], v[40:41], 0, s[10:11]
	v_cvt_pk_bf16_f32 v42, v52, s0
	global_store_short v[40:41], v42, off
	v_lshl_add_u64 v[40:41], v[40:41], 0, s[10:11]
	v_cvt_pk_bf16_f32 v42, v53, s0
	global_store_short v[40:41], v42, off
	v_lshl_add_u64 v[40:41], v[40:41], 0, s[10:11]
	v_cvt_pk_bf16_f32 v42, v50, s0
	global_store_short v[40:41], v42, off
	v_lshl_add_u64 v[40:41], v[40:41], 0, s[10:11]
	v_cvt_pk_bf16_f32 v42, v51, s0
	global_store_short v[40:41], v42, off
	v_lshl_add_u64 v[40:41], v[40:41], 0, s[10:11]
	v_pk_add_f32 v[42:43], v[32:33], v[92:93]
	v_pk_add_f32 v[40:41], v[34:35], v[94:95]
	v_cvt_pk_bf16_f32 v32, v36, v37
	v_cvt_pk_bf16_f32 v33, v38, v39
	v_cvt_pk_bf16_f32 v34, v42, v43
	v_cvt_pk_bf16_f32 v35, v40, v41
	global_store_dwordx4 v[54:55], v[32:35], off offset:256
	v_pk_add_f32 v[30:31], v[30:31], v[118:119]
	v_pk_add_f32 v[28:29], v[28:29], v[116:117]
	v_add_u32_e32 v32, v128, v49
	v_ashrrev_i32_e32 v33, 31, v32
	v_lshlrev_b64 v[32:33], 15, v[32:33]
	v_or3_b32 v32, v32, v56, v129
	v_lshlrev_b64 v[32:33], 7, v[32:33]
	v_lshl_add_u64 v[32:33], s[92:93], 0, v[32:33]
	v_lshl_add_u64 v[32:33], v[32:33], 0, v[152:153]
	v_cvt_pk_bf16_f32 v34, v36, s0
	global_store_short v[32:33], v34, off
	v_lshl_add_u64 v[32:33], v[32:33], 0, s[10:11]
	v_cvt_pk_bf16_f32 v34, v37, s0
	global_store_short v[32:33], v34, off
	v_lshl_add_u64 v[32:33], v[32:33], 0, s[10:11]
	v_cvt_pk_bf16_f32 v34, v38, s0
	global_store_short v[32:33], v34, off
	v_lshl_add_u64 v[32:33], v[32:33], 0, s[10:11]
	v_cvt_pk_bf16_f32 v34, v39, s0
	global_store_short v[32:33], v34, off
	v_lshl_add_u64 v[32:33], v[32:33], 0, s[10:11]
	v_cvt_pk_bf16_f32 v34, v42, s0
	global_store_short v[32:33], v34, off
	v_lshl_add_u64 v[32:33], v[32:33], 0, s[10:11]
	v_cvt_pk_bf16_f32 v34, v43, s0
	global_store_short v[32:33], v34, off
	v_lshl_add_u64 v[32:33], v[32:33], 0, s[10:11]
	v_cvt_pk_bf16_f32 v34, v40, s0
	global_store_short v[32:33], v34, off
	v_lshl_add_u64 v[32:33], v[32:33], 0, s[10:11]
	v_cvt_pk_bf16_f32 v34, v41, s0
	global_store_short v[32:33], v34, off
	v_lshl_add_u64 v[32:33], v[32:33], 0, s[10:11]
	v_pk_add_f32 v[34:35], v[26:27], v[114:115]
	v_add_u32_e32 v32, 0xa0, v162
	v_ashrrev_i32_e32 v33, 31, v32
	v_lshlrev_b64 v[38:39], 11, v[32:33]
	v_pk_add_f32 v[36:37], v[24:25], v[112:113]
	v_lshl_add_u64 v[38:39], s[18:19], 0, v[38:39]
	v_cvt_pk_bf16_f32 v24, v28, v29
	v_cvt_pk_bf16_f32 v25, v30, v31
	v_cvt_pk_bf16_f32 v26, v36, v37
	v_cvt_pk_bf16_f32 v27, v34, v35
	v_lshl_add_u64 v[38:39], v[38:39], 0, v[166:167]
	global_store_dwordx4 v[38:39], v[24:27], off
	v_pk_add_f32 v[22:23], v[22:23], v[98:99]
	v_pk_add_f32 v[20:21], v[20:21], v[96:97]
	v_ashrrev_i32_e32 v24, 11, v32
	v_and_b32_e32 v33, -4, v24
; DI unsigned short f2bf(float x) { return (unsigned short)(pk2(x, 0.f) & 0xffffu); }
; DI uint4 pk8(f32x4 a, f32x4 b) { return make_uint4(pk2(a[0], a[1]), pk2(a[2], a[3]), pk2(b[0], b[1]), pk2(b[2], b[3])); }
;     DI void operator()(const f32x4 (&acc)[2][2][4][2], const pg8::Unit& u, int wr, int wc, int fr, int fq) const {
;     ...
;         const int t0 = u.pm * 256 + wr * 64 + fr;
;         if (pn < 4) {
; #pragma unroll
;             for (int i = 0; i < 16; ++i) {
;                 const int ai = TILE_AI(i), m = TILE_M(i), bj = TILE_BJ(i);
;                 const int t = t0 + ai * 128 + m * 16, col = colb + bj * 128;
;                 const f32x4 v0 = acc[ai][bj][m][0] + bia[bj][0], v1 = acc[ai][bj][m][1] + bia[bj][1];
;                 *(uint4*)(xm + (size_t)t * 1024 + col) = pk8(v0, v1);
;                 const int b = t >> 13, sidx = t & 8191;
;                 bf16_t* tp = xmT + ((((size_t)(b * 4 + (col >> 8)) * 128 + (sidx >> 6)) * 256 + (col & 255)) * 64) + (sidx & 63);
; #pragma unroll
;                 for (int r = 0; r < 4; ++r) { *tp = f2bf(v0[r]); tp += 64; asm volatile("" : "+v"(tp)); }
; #pragma unroll
;                 for (int r = 0; r < 4; ++r) { *tp = f2bf(v1[r]); tp += 64; asm volatile("" : "+v"(tp)); }
;             }
	v_add_u32_e32 v24, v163, v33
	v_ashrrev_i32_e32 v25, 31, v24
	v_lshlrev_b32_e32 v26, 2, v32
	v_lshlrev_b64 v[24:25], 15, v[24:25]
	v_and_b32_e32 v40, 0x7f00, v26
	v_or3_b32 v24, v24, v40, v165
	v_lshlrev_b64 v[24:25], 7, v[24:25]
	v_and_b32_e32 v26, 63, v32
	v_lshl_add_u64 v[24:25], s[92:93], 0, v[24:25]
	v_lshlrev_b32_e32 v152, 1, v26
	v_lshl_add_u64 v[24:25], v[24:25], 0, v[152:153]
	v_cvt_pk_bf16_f32 v26, v28, s0
	global_store_short v[24:25], v26, off
	v_lshl_add_u64 v[24:25], v[24:25], 0, s[10:11]
	v_cvt_pk_bf16_f32 v26, v29, s0
	global_store_short v[24:25], v26, off
	v_lshl_add_u64 v[24:25], v[24:25], 0, s[10:11]
	v_cvt_pk_bf16_f32 v26, v30, s0
	global_store_short v[24:25], v26, off
	v_lshl_add_u64 v[24:25], v[24:25], 0, s[10:11]
	v_cvt_pk_bf16_f32 v26, v31, s0
	global_store_short v[24:25], v26, off
	v_lshl_add_u64 v[24:25], v[24:25], 0, s[10:11]
	v_cvt_pk_bf16_f32 v26, v36, s0
	global_store_short v[24:25], v26, off
	v_lshl_add_u64 v[24:25], v[24:25], 0, s[10:11]
	v_cvt_pk_bf16_f32 v26, v37, s0
	global_store_short v[24:25], v26, off
	v_lshl_add_u64 v[24:25], v[24:25], 0, s[10:11]
	v_cvt_pk_bf16_f32 v26, v34, s0
	global_store_short v[24:25], v26, off
	v_lshl_add_u64 v[24:25], v[24:25], 0, s[10:11]
	v_cvt_pk_bf16_f32 v26, v35, s0
	global_store_short v[24:25], v26, off
	v_lshl_add_u64 v[24:25], v[24:25], 0, s[10:11]
	v_pk_add_f32 v[26:27], v[16:17], v[92:93]
	v_pk_add_f32 v[24:25], v[18:19], v[94:95]
	v_cvt_pk_bf16_f32 v16, v20, v21
	v_cvt_pk_bf16_f32 v17, v22, v23
	v_cvt_pk_bf16_f32 v18, v26, v27
	v_cvt_pk_bf16_f32 v19, v24, v25
	global_store_dwordx4 v[38:39], v[16:19], off offset:256
	v_pk_add_f32 v[14:15], v[14:15], v[118:119]
	v_pk_add_f32 v[12:13], v[12:13], v[116:117]
	v_add_u32_e32 v16, v128, v33
	v_ashrrev_i32_e32 v17, 31, v16
	v_lshlrev_b64 v[16:17], 15, v[16:17]
	v_or3_b32 v16, v16, v40, v129
	v_lshlrev_b64 v[16:17], 7, v[16:17]
	v_lshl_add_u64 v[16:17], s[92:93], 0, v[16:17]
	v_lshl_add_u64 v[16:17], v[16:17], 0, v[152:153]
	v_cvt_pk_bf16_f32 v18, v20, s0
	global_store_short v[16:17], v18, off
	v_lshl_add_u64 v[16:17], v[16:17], 0, s[10:11]
	v_cvt_pk_bf16_f32 v18, v21, s0
	global_store_short v[16:17], v18, off
	v_lshl_add_u64 v[16:17], v[16:17], 0, s[10:11]
	v_cvt_pk_bf16_f32 v18, v22, s0
	global_store_short v[16:17], v18, off
	v_lshl_add_u64 v[16:17], v[16:17], 0, s[10:11]
	v_cvt_pk_bf16_f32 v18, v23, s0
	global_store_short v[16:17], v18, off
	v_lshl_add_u64 v[16:17], v[16:17], 0, s[10:11]
	v_cvt_pk_bf16_f32 v18, v26, s0
	global_store_short v[16:17], v18, off
	v_lshl_add_u64 v[16:17], v[16:17], 0, s[10:11]
	v_cvt_pk_bf16_f32 v18, v27, s0
	global_store_short v[16:17], v18, off
	v_lshl_add_u64 v[16:17], v[16:17], 0, s[10:11]
	v_cvt_pk_bf16_f32 v18, v24, s0
	global_store_short v[16:17], v18, off
	v_lshl_add_u64 v[16:17], v[16:17], 0, s[10:11]
	v_cvt_pk_bf16_f32 v18, v25, s0
	global_store_short v[16:17], v18, off
	v_lshl_add_u64 v[16:17], v[16:17], 0, s[10:11]
	v_pk_add_f32 v[18:19], v[10:11], v[114:115]
	v_add_u32_e32 v16, 0xb0, v162
	v_ashrrev_i32_e32 v17, 31, v16
	v_lshlrev_b64 v[22:23], 11, v[16:17]
	v_pk_add_f32 v[20:21], v[8:9], v[112:113]
	v_lshl_add_u64 v[22:23], s[18:19], 0, v[22:23]
	v_cvt_pk_bf16_f32 v8, v12, v13
	v_cvt_pk_bf16_f32 v9, v14, v15
	v_cvt_pk_bf16_f32 v10, v20, v21
	v_cvt_pk_bf16_f32 v11, v18, v19
	v_lshl_add_u64 v[22:23], v[22:23], 0, v[166:167]
	global_store_dwordx4 v[22:23], v[8:11], off
	v_pk_add_f32 v[6:7], v[6:7], v[98:99]
	v_pk_add_f32 v[4:5], v[4:5], v[96:97]
	v_ashrrev_i32_e32 v8, 11, v16
	v_and_b32_e32 v17, -4, v8
	v_add_u32_e32 v8, v163, v17
	v_ashrrev_i32_e32 v9, 31, v8
	v_lshlrev_b32_e32 v10, 2, v16
	v_lshlrev_b64 v[8:9], 15, v[8:9]
	v_and_b32_e32 v24, 0x7f00, v10
	v_or3_b32 v8, v8, v24, v165
	v_lshlrev_b64 v[8:9], 7, v[8:9]
	v_and_b32_e32 v10, 63, v16
	v_lshl_add_u64 v[8:9], s[92:93], 0, v[8:9]
	v_lshlrev_b32_e32 v152, 1, v10
	v_lshl_add_u64 v[8:9], v[8:9], 0, v[152:153]
	v_cvt_pk_bf16_f32 v10, v12, s0
	global_store_short v[8:9], v10, off
	v_lshl_add_u64 v[8:9], v[8:9], 0, s[10:11]
	v_cvt_pk_bf16_f32 v10, v13, s0
	global_store_short v[8:9], v10, off
	v_lshl_add_u64 v[8:9], v[8:9], 0, s[10:11]
	v_cvt_pk_bf16_f32 v10, v14, s0
	global_store_short v[8:9], v10, off
	v_lshl_add_u64 v[8:9], v[8:9], 0, s[10:11]
	v_cvt_pk_bf16_f32 v10, v15, s0
	global_store_short v[8:9], v10, off
	v_lshl_add_u64 v[8:9], v[8:9], 0, s[10:11]
	v_cvt_pk_bf16_f32 v10, v20, s0
	global_store_short v[8:9], v10, off
	v_lshl_add_u64 v[8:9], v[8:9], 0, s[10:11]
	v_cvt_pk_bf16_f32 v10, v21, s0
	global_store_short v[8:9], v10, off
	v_lshl_add_u64 v[8:9], v[8:9], 0, s[10:11]
	v_cvt_pk_bf16_f32 v10, v18, s0
	global_store_short v[8:9], v10, off
	v_lshl_add_u64 v[8:9], v[8:9], 0, s[10:11]
	v_cvt_pk_bf16_f32 v10, v19, s0
	global_store_short v[8:9], v10, off
	v_lshl_add_u64 v[8:9], v[8:9], 0, s[10:11]
	v_pk_add_f32 v[10:11], v[0:1], v[92:93]
	v_pk_add_f32 v[8:9], v[2:3], v[94:95]
	v_cvt_pk_bf16_f32 v0, v4, v5
	v_cvt_pk_bf16_f32 v1, v6, v7
	v_cvt_pk_bf16_f32 v2, v10, v11
	v_cvt_pk_bf16_f32 v3, v8, v9
	global_store_dwordx4 v[22:23], v[0:3], off offset:256
	s_nop 1
	v_add_u32_e32 v0, v128, v17
	v_ashrrev_i32_e32 v1, 31, v0
	v_lshlrev_b64 v[0:1], 15, v[0:1]
	v_or3_b32 v0, v0, v24, v129
	v_lshlrev_b64 v[0:1], 7, v[0:1]
	v_lshl_add_u64 v[0:1], s[92:93], 0, v[0:1]
	v_lshl_add_u64 v[0:1], v[0:1], 0, v[152:153]
	v_cvt_pk_bf16_f32 v2, v4, s0
	global_store_short v[0:1], v2, off
	v_lshl_add_u64 v[0:1], v[0:1], 0, s[10:11]
	v_cvt_pk_bf16_f32 v2, v5, s0
	global_store_short v[0:1], v2, off
	v_lshl_add_u64 v[0:1], v[0:1], 0, s[10:11]
	v_cvt_pk_bf16_f32 v2, v6, s0
	global_store_short v[0:1], v2, off
	v_lshl_add_u64 v[0:1], v[0:1], 0, s[10:11]
	v_cvt_pk_bf16_f32 v2, v7, s0
	global_store_short v[0:1], v2, off
	v_lshl_add_u64 v[0:1], v[0:1], 0, s[10:11]
	v_cvt_pk_bf16_f32 v2, v10, s0
	global_store_short v[0:1], v2, off
	v_lshl_add_u64 v[0:1], v[0:1], 0, s[10:11]
	v_cvt_pk_bf16_f32 v2, v11, s0
	global_store_short v[0:1], v2, off
	v_lshl_add_u64 v[0:1], v[0:1], 0, s[10:11]
	v_cvt_pk_bf16_f32 v2, v8, s0
	global_store_short v[0:1], v2, off
	v_lshl_add_u64 v[0:1], v[0:1], 0, s[10:11]
	v_cvt_pk_bf16_f32 v2, v9, s0
	global_store_short v[0:1], v2, off
	v_lshl_add_u64 v[0:1], v[0:1], 0, s[10:11]
	s_andn2_b64 vcc, exec, s[0:1]
	s_mov_b64 s[0:1], -1
	s_cbranch_vccnz .LBB0_279

; DI uint4 pk8(f32x4 a, f32x4 b) { return make_uint4(pk2(a[0], a[1]), pk2(a[2], a[3]), pk2(b[0], b[1]), pk2(b[2], b[3])); }
;     DI void operator()(const f32x4 (&acc)[2][2][4][2], const pg8::Unit& u, int wr, int wc, int fr, int fq) const {
;         const int h = u.pn;
;         const int d = wc * 32 + 8 * fq;
;         const int t0 = u.pm * 256 + wr * 64 + fr;
;         const int b = t0 >> 13, bh = b * 4 + h, s0 = t0 & 8191;
;         bf16_t* qp = q + ((size_t)bh * 8192 + s0) * 128 + d;
; #pragma unroll
;         for (int ai = 0; ai < 2; ++ai)
; #pragma unroll
;             for (int m = 0; m < 4; ++m) {
;                 f32x4 q0 = acc[ai][0][m][0] * 0.08838834764831845f, q1 = acc[ai][0][m][1] * 0.08838834764831845f;
;                 *(uint4*)(qp + (size_t)(ai * 128 + m * 16) * 128) = pk8(q0, q1);
;             }
;         bf16_t* kp = k + ((size_t)bh * 8192 + s0) * 128 + d;
; #pragma unroll
;         for (int ai = 0; ai < 2; ++ai)
; #pragma unroll
;             for (int m = 0; m < 4; ++m) *(uint4*)(kp + (size_t)(ai * 128 + m * 16) * 128) = pk8(acc[ai][1][m][0], acc[ai][1][m][1]);
;         bf16_t* tp0 = kT + (((size_t)bh * 128 + (s0 >> 6)) * 128 + d) * 64 + (s0 & 63);
.LBB0_468:
	v_mov_b32_e32 v158, v146
	v_mov_b32_e32 v136, v147
	s_lshl_b32 s18, s36, 8
	s_add_i32 s18, s18, s51
	v_lshl_add_u32 v142, v136, 3, s52
	v_add_u32_e32 v136, s18, v158
	v_ashrrev_i32_e32 v138, 11, v136
	v_and_b32_e32 v138, -4, v138
	v_add_u32_e32 v138, s93, v138
	v_ashrrev_i32_e32 v139, 31, v138
	v_and_b32_e32 v143, 0x1fff, v136
	v_lshlrev_b64 v[144:145], 21, v[138:139]
	v_lshl_or_b32 v138, v143, 8, v144
	v_mov_b32_e32 v139, v145
	v_ashrrev_i32_e32 v143, 31, v142
	v_lshl_add_u64 v[152:153], s[76:77], 0, v[138:139]
	v_lshlrev_b64 v[154:155], 1, v[142:143]
	v_pk_mul_f32 v[126:127], v[126:127], s[24:25] op_sel_hi:[1,0]
	v_pk_mul_f32 v[124:125], v[124:125], s[24:25] op_sel_hi:[1,0]
	v_pk_mul_f32 v[156:157], v[122:123], s[24:25] op_sel_hi:[1,0]
	v_pk_mul_f32 v[122:123], v[120:121], s[24:25] op_sel_hi:[1,0]
	v_lshl_add_u64 v[152:153], v[152:153], 0, v[154:155]
	v_cvt_pk_bf16_f32 v120, v124, v125
	v_cvt_pk_bf16_f32 v121, v126, v127
	v_cvt_pk_bf16_f32 v122, v122, v123
	v_cvt_pk_bf16_f32 v123, v156, v157
	v_pk_mul_f32 v[108:109], v[108:109], s[24:25] op_sel_hi:[1,0]
	global_store_dwordx4 v[152:153], v[120:123], off
	v_pk_mul_f32 v[110:111], v[110:111], s[24:25] op_sel_hi:[1,0]
	v_pk_mul_f32 v[94:95], v[94:95], s[24:25] op_sel_hi:[1,0]
	v_pk_mul_f32 v[120:121], v[106:107], s[24:25] op_sel_hi:[1,0]
	v_pk_mul_f32 v[106:107], v[104:105], s[24:25] op_sel_hi:[1,0]
	v_cvt_pk_bf16_f32 v104, v108, v109
	v_add_co_u32_e32 v108, vcc, s50, v152
	v_cvt_pk_bf16_f32 v105, v110, v111
	v_cvt_pk_bf16_f32 v106, v106, v107
	v_cvt_pk_bf16_f32 v107, v120, v121
	v_addc_co_u32_e32 v109, vcc, 0, v153, vcc
	global_store_dwordx4 v[108:109], v[104:107], off offset:-4096
	v_pk_mul_f32 v[92:93], v[92:93], s[24:25] op_sel_hi:[1,0]
	v_pk_mul_f32 v[76:77], v[76:77], s[24:25] op_sel_hi:[1,0]
	v_pk_mul_f32 v[104:105], v[90:91], s[24:25] op_sel_hi:[1,0]
	v_pk_mul_f32 v[90:91], v[88:89], s[24:25] op_sel_hi:[1,0]
	v_cvt_pk_bf16_f32 v88, v92, v93
	v_cvt_pk_bf16_f32 v89, v94, v95
	v_cvt_pk_bf16_f32 v90, v90, v91
	v_cvt_pk_bf16_f32 v91, v104, v105
	global_store_dwordx4 v[108:109], v[88:91], off
	v_pk_mul_f32 v[78:79], v[78:79], s[24:25] op_sel_hi:[1,0]
	v_pk_mul_f32 v[70:71], v[70:71], s[24:25] op_sel_hi:[1,0]
	v_pk_mul_f32 v[88:89], v[74:75], s[24:25] op_sel_hi:[1,0]
	v_pk_mul_f32 v[74:75], v[72:73], s[24:25] op_sel_hi:[1,0]
	v_cvt_pk_bf16_f32 v72, v76, v77
	v_add_co_u32_e32 v76, vcc, s87, v152
	v_cvt_pk_bf16_f32 v73, v78, v79
	v_cvt_pk_bf16_f32 v74, v74, v75
	v_cvt_pk_bf16_f32 v75, v88, v89
	v_addc_co_u32_e32 v77, vcc, 0, v153, vcc
	global_store_dwordx4 v[76:77], v[72:75], off
	v_pk_mul_f32 v[76:77], v[114:115], s[24:25] op_sel_hi:[1,0]
	v_pk_mul_f32 v[78:79], v[112:113], s[24:25] op_sel_hi:[1,0]
	v_pk_mul_f32 v[74:75], v[118:119], s[24:25] op_sel_hi:[1,0]
	v_pk_mul_f32 v[72:73], v[116:117], s[24:25] op_sel_hi:[1,0]
	v_pk_mul_f32 v[88:89], v[96:97], s[24:25] op_sel_hi:[1,0]
	v_cvt_pk_bf16_f32 v72, v72, v73
	v_cvt_pk_bf16_f32 v73, v74, v75
	v_cvt_pk_bf16_f32 v75, v76, v77
	v_add_co_u32_e32 v76, vcc, s91, v152
	v_cvt_pk_bf16_f32 v74, v78, v79
	s_nop 0
	v_addc_co_u32_e32 v77, vcc, 0, v153, vcc
	global_store_dwordx4 v[76:77], v[72:75], off offset:-4096
	v_pk_mul_f32 v[78:79], v[98:99], s[24:25] op_sel_hi:[1,0]
	v_pk_mul_f32 v[68:69], v[68:69], s[24:25] op_sel_hi:[1,0]
	v_pk_mul_f32 v[74:75], v[102:103], s[24:25] op_sel_hi:[1,0]
	v_pk_mul_f32 v[72:73], v[100:101], s[24:25] op_sel_hi:[1,0]
	s_mov_b64 s[18:19], 0x60
	v_cvt_pk_bf16_f32 v72, v72, v73
	v_cvt_pk_bf16_f32 v73, v74, v75
	v_cvt_pk_bf16_f32 v74, v88, v89
	v_cvt_pk_bf16_f32 v75, v78, v79
	global_store_dwordx4 v[76:77], v[72:75], off
	v_pk_mul_f32 v[76:77], v[82:83], s[24:25] op_sel_hi:[1,0]
	v_pk_mul_f32 v[78:79], v[80:81], s[24:25] op_sel_hi:[1,0]
	v_pk_mul_f32 v[74:75], v[86:87], s[24:25] op_sel_hi:[1,0]
	v_pk_mul_f32 v[72:73], v[84:85], s[24:25] op_sel_hi:[1,0]
	v_readlane_b32 s94, v254, 62
	v_cvt_pk_bf16_f32 v72, v72, v73
	v_cvt_pk_bf16_f32 v73, v74, v75
	v_cvt_pk_bf16_f32 v75, v76, v77
	v_add_co_u32_e32 v76, vcc, s92, v152
	v_cvt_pk_bf16_f32 v74, v78, v79
	s_nop 0
	v_addc_co_u32_e32 v77, vcc, 0, v153, vcc
	global_store_dwordx4 v[76:77], v[72:75], off offset:-4096
	v_readlane_b32 s95, v254, 63
	v_mov_b32_e32 v250, v140
	v_pk_mul_f32 v[72:73], v[66:67], s[24:25] op_sel_hi:[1,0]
	v_pk_mul_f32 v[66:67], v[64:65], s[24:25] op_sel_hi:[1,0]
	v_cvt_pk_bf16_f32 v64, v68, v69
	v_cvt_pk_bf16_f32 v65, v70, v71
	v_cvt_pk_bf16_f32 v66, v66, v67
	v_cvt_pk_bf16_f32 v67, v72, v73
	global_store_dwordx4 v[76:77], v[64:67], off
	s_nop 1
	v_lshl_add_u64 v[64:65], s[78:79], 0, v[138:139]
	v_lshl_add_u64 v[68:69], v[64:65], 0, v[154:155]
	v_cvt_pk_bf16_f32 v64, v60, v61
	v_cvt_pk_bf16_f32 v65, v62, v63
	v_cvt_pk_bf16_f32 v66, v56, v57
	v_cvt_pk_bf16_f32 v67, v58, v59
	v_add_co_u32_e32 v70, vcc, s50, v68
	global_store_dwordx4 v[68:69], v[64:67], off
	s_nop 0
	v_addc_co_u32_e32 v71, vcc, 0, v69, vcc
	v_cvt_pk_bf16_f32 v64, v52, v53
	v_cvt_pk_bf16_f32 v65, v54, v55
	v_cvt_pk_bf16_f32 v66, v48, v49
	v_cvt_pk_bf16_f32 v67, v50, v51
	global_store_dwordx4 v[70:71], v[64:67], off offset:-4096
	v_cvt_pk_bf16_f32 v60, v60, s0
	v_cvt_pk_bf16_f32 v62, v62, s0
	v_cvt_pk_bf16_f32 v64, v44, v45
	v_cvt_pk_bf16_f32 v65, v46, v47
	v_cvt_pk_bf16_f32 v66, v40, v41
	v_cvt_pk_bf16_f32 v67, v42, v43
	global_store_dwordx4 v[70:71], v[64:67], off
	v_add_co_u32_e32 v70, vcc, s87, v68
	s_nop 0
	v_cvt_pk_bf16_f32 v64, v32, v33
	v_cvt_pk_bf16_f32 v65, v34, v35
	v_cvt_pk_bf16_f32 v66, v24, v25
	v_cvt_pk_bf16_f32 v67, v26, v27
	v_addc_co_u32_e32 v71, vcc, 0, v69, vcc
	global_store_dwordx4 v[70:71], v[64:67], off
	v_add_co_u32_e32 v70, vcc, s91, v68
	s_nop 0
; DI unsigned short f2bf(float x) { return (unsigned short)(pk2(x, 0.f) & 0xffffu); }
; DI uint4 pk8(f32x4 a, f32x4 b) { return make_uint4(pk2(a[0], a[1]), pk2(a[2], a[3]), pk2(b[0], b[1]), pk2(b[2], b[3])); }
;     DI void operator()(const f32x4 (&acc)[2][2][4][2], const pg8::Unit& u, int wr, int wc, int fr, int fq) const {
;     ...
;         bf16_t* kp = k + ((size_t)bh * 8192 + s0) * 128 + d;
; #pragma unroll
;         for (int ai = 0; ai < 2; ++ai)
; #pragma unroll
;             for (int m = 0; m < 4; ++m) *(uint4*)(kp + (size_t)(ai * 128 + m * 16) * 128) = pk8(acc[ai][1][m][0], acc[ai][1][m][1]);
;         bf16_t* tp0 = kT + (((size_t)bh * 128 + (s0 >> 6)) * 128 + d) * 64 + (s0 & 63);
; #pragma unroll
;         for (int ai = 0; ai < 2; ++ai)
; #pragma unroll
;             for (int m = 0; m < 4; ++m) {
;                 bf16_t* tp = tp0 + (size_t)(ai * 2 + (m >> 2)) * 0 + ((ai * 128 + m * 16) >> 6) * (128 * 64) + ((ai * 128 + m * 16) & 63);
;                 asm volatile("" : "+v"(tp));
; #pragma unroll
;                 for (int r = 0; r < 4; ++r) { *tp = f2bf(acc[ai][1][m][0][r]); tp += 64; asm volatile("" : "+v"(tp)); }
; #pragma unroll
;                 for (int r = 0; r < 4; ++r) { *tp = f2bf(acc[ai][1][m][1][r]); tp += 64; asm volatile("" : "+v"(tp)); }
	v_cvt_pk_bf16_f32 v64, v36, v37
	v_cvt_pk_bf16_f32 v65, v38, v39
	v_cvt_pk_bf16_f32 v66, v28, v29
	v_cvt_pk_bf16_f32 v67, v30, v31
	v_addc_co_u32_e32 v71, vcc, 0, v69, vcc
	global_store_dwordx4 v[70:71], v[64:67], off offset:-4096
	v_add_co_u32_e32 v68, vcc, s92, v68
	s_nop 0
	v_cvt_pk_bf16_f32 v64, v20, v21
	v_cvt_pk_bf16_f32 v65, v22, v23
	v_cvt_pk_bf16_f32 v66, v16, v17
	v_cvt_pk_bf16_f32 v67, v18, v19
	global_store_dwordx4 v[70:71], v[64:67], off
	v_addc_co_u32_e32 v69, vcc, 0, v69, vcc
	s_nop 0
	v_cvt_pk_bf16_f32 v64, v12, v13
	v_cvt_pk_bf16_f32 v65, v14, v15
	v_cvt_pk_bf16_f32 v66, v8, v9
	v_cvt_pk_bf16_f32 v67, v10, v11
	global_store_dwordx4 v[68:69], v[64:67], off offset:-4096
	v_cvt_pk_bf16_f32 v56, v56, s0
	v_cvt_pk_bf16_f32 v58, v58, s0
	v_cvt_pk_bf16_f32 v64, v4, v5
	v_cvt_pk_bf16_f32 v65, v6, v7
	v_cvt_pk_bf16_f32 v66, v0, v1
	v_cvt_pk_bf16_f32 v67, v2, v3
	global_store_dwordx4 v[68:69], v[64:67], off
	v_cvt_pk_bf16_f32 v52, v52, s0
	v_cvt_pk_bf16_f32 v54, v54, s0
	v_lshlrev_b32_e32 v64, 1, v136
	v_and_b32_e32 v136, 0x3f80, v64
	v_lshl_add_u64 v[64:65], v[136:137], 0, v[142:143]
	v_lshlrev_b64 v[64:65], 7, v[64:65]
	v_lshl_add_u64 v[66:67], s[6:7], 0, v[144:145]
	v_lshl_add_u64 v[64:65], v[66:67], 0, v[64:65]
	v_and_b32_e32 v66, 63, v158
	v_lshlrev_b32_e32 v136, 1, v66
	v_lshl_add_u64 v[64:65], v[64:65], 0, v[136:137]
	v_mov_b64_e32 v[66:67], v[64:65]
	global_store_short v[66:67], v60, off
	v_lshl_add_u64 v[66:67], v[66:67], 0, s[8:9]
	v_cvt_pk_bf16_f32 v60, v61, s0
	global_store_short v[66:67], v60, off
	v_lshl_add_u64 v[60:61], v[66:67], 0, s[8:9]
	global_store_short v[60:61], v62, off
	v_lshl_add_u64 v[60:61], v[60:61], 0, s[8:9]
	v_cvt_pk_bf16_f32 v62, v63, s0
	global_store_short v[60:61], v62, off
	v_lshl_add_u64 v[60:61], v[60:61], 0, s[8:9]
	global_store_short v[60:61], v56, off
	v_lshl_add_u64 v[60:61], v[60:61], 0, s[8:9]
	v_cvt_pk_bf16_f32 v56, v57, s0
	global_store_short v[60:61], v56, off
	v_lshl_add_u64 v[56:57], v[60:61], 0, s[8:9]
	global_store_short v[56:57], v58, off
	v_lshl_add_u64 v[56:57], v[56:57], 0, s[8:9]
	v_cvt_pk_bf16_f32 v58, v59, s0
	global_store_short v[56:57], v58, off
	v_lshl_add_u64 v[56:57], v[56:57], 0, s[8:9]
	v_cvt_pk_bf16_f32 v48, v48, s0
	v_lshl_add_u64 v[56:57], v[64:65], 0, 32
	global_store_short v[56:57], v52, off
	v_lshl_add_u64 v[56:57], v[56:57], 0, s[8:9]
	v_cvt_pk_bf16_f32 v52, v53, s0
	global_store_short v[56:57], v52, off
	v_lshl_add_u64 v[52:53], v[56:57], 0, s[8:9]
	global_store_short v[52:53], v54, off
	v_lshl_add_u64 v[52:53], v[52:53], 0, s[8:9]
	v_cvt_pk_bf16_f32 v54, v55, s0
	global_store_short v[52:53], v54, off
	v_lshl_add_u64 v[52:53], v[52:53], 0, s[8:9]
	global_store_short v[52:53], v48, off
	v_lshl_add_u64 v[52:53], v[52:53], 0, s[8:9]
	v_cvt_pk_bf16_f32 v48, v49, s0
	global_store_short v[52:53], v48, off
	v_lshl_add_u64 v[48:49], v[52:53], 0, s[8:9]
	v_cvt_pk_bf16_f32 v50, v50, s0
	global_store_short v[48:49], v50, off
	v_lshl_add_u64 v[48:49], v[48:49], 0, s[8:9]
	v_cvt_pk_bf16_f32 v50, v51, s0
	global_store_short v[48:49], v50, off
	v_lshl_add_u64 v[48:49], v[48:49], 0, s[8:9]
	v_cvt_pk_bf16_f32 v44, v44, s0
	v_lshl_add_u64 v[48:49], v[64:65], 0, 64
	global_store_short v[48:49], v44, off
	v_lshl_add_u64 v[48:49], v[48:49], 0, s[8:9]
	v_cvt_pk_bf16_f32 v44, v45, s0
	global_store_short v[48:49], v44, off
	v_lshl_add_u64 v[44:45], v[48:49], 0, s[8:9]
	v_cvt_pk_bf16_f32 v46, v46, s0
	global_store_short v[44:45], v46, off
	v_lshl_add_u64 v[44:45], v[44:45], 0, s[8:9]
	v_cvt_pk_bf16_f32 v46, v47, s0
	global_store_short v[44:45], v46, off
	v_lshl_add_u64 v[44:45], v[44:45], 0, s[8:9]
	v_cvt_pk_bf16_f32 v40, v40, s0
	global_store_short v[44:45], v40, off
	v_lshl_add_u64 v[44:45], v[44:45], 0, s[8:9]
	v_cvt_pk_bf16_f32 v40, v41, s0
	global_store_short v[44:45], v40, off
	v_lshl_add_u64 v[40:41], v[44:45], 0, s[8:9]
	v_cvt_pk_bf16_f32 v42, v42, s0
	global_store_short v[40:41], v42, off
	v_lshl_add_u64 v[40:41], v[40:41], 0, s[8:9]
	v_cvt_pk_bf16_f32 v42, v43, s0
	global_store_short v[40:41], v42, off
	v_lshl_add_u64 v[40:41], v[40:41], 0, s[8:9]
	v_cvt_pk_bf16_f32 v32, v32, s0
	v_lshl_add_u64 v[40:41], v[64:65], 0, s[18:19]
	global_store_short v[40:41], v32, off
	v_lshl_add_u64 v[40:41], v[40:41], 0, s[8:9]
	v_cvt_pk_bf16_f32 v32, v33, s0
	global_store_short v[40:41], v32, off
	v_lshl_add_u64 v[32:33], v[40:41], 0, s[8:9]
	v_cvt_pk_bf16_f32 v34, v34, s0
	global_store_short v[32:33], v34, off
	v_lshl_add_u64 v[32:33], v[32:33], 0, s[8:9]
	v_cvt_pk_bf16_f32 v34, v35, s0
	global_store_short v[32:33], v34, off
	v_lshl_add_u64 v[32:33], v[32:33], 0, s[8:9]
; DI unsigned short f2bf(float x) { return (unsigned short)(pk2(x, 0.f) & 0xffffu); }
; #define PG8_BAR __builtin_amdgcn_s_barrier()
; template <class Epi>
; DI void gemm_phase(PG8_LAS unsigned char* lds, const Gemm g, const StaticOrder& S, const Epi& E) {
;     ...
;         if (wr == 1) PG8_BAR;
;     DI void operator()(const f32x4 (&acc)[2][2][4][2], const pg8::Unit& u, int wr, int wc, int fr, int fq) const {
;     ...
;         bf16_t* tp0 = kT + (((size_t)bh * 128 + (s0 >> 6)) * 128 + d) * 64 + (s0 & 63);
; #pragma unroll
;         for (int ai = 0; ai < 2; ++ai)
; #pragma unroll
;             for (int m = 0; m < 4; ++m) {
;                 bf16_t* tp = tp0 + (size_t)(ai * 2 + (m >> 2)) * 0 + ((ai * 128 + m * 16) >> 6) * (128 * 64) + ((ai * 128 + m * 16) & 63);
;                 asm volatile("" : "+v"(tp));
; #pragma unroll
;                 for (int r = 0; r < 4; ++r) { *tp = f2bf(acc[ai][1][m][0][r]); tp += 64; asm volatile("" : "+v"(tp)); }
; #pragma unroll
;                 for (int r = 0; r < 4; ++r) { *tp = f2bf(acc[ai][1][m][1][r]); tp += 64; asm volatile("" : "+v"(tp)); }
;             }
	v_cvt_pk_bf16_f32 v24, v24, s0
	global_store_short v[32:33], v24, off
	v_lshl_add_u64 v[32:33], v[32:33], 0, s[8:9]
	v_cvt_pk_bf16_f32 v24, v25, s0
	global_store_short v[32:33], v24, off
	v_lshl_add_u64 v[24:25], v[32:33], 0, s[8:9]
	v_cvt_pk_bf16_f32 v26, v26, s0
	global_store_short v[24:25], v26, off
	v_lshl_add_u64 v[24:25], v[24:25], 0, s[8:9]
	v_cvt_pk_bf16_f32 v26, v27, s0
	global_store_short v[24:25], v26, off
	v_lshl_add_u64 v[24:25], v[24:25], 0, s[8:9]
	s_mov_b64 s[18:19], 0x8000
	v_lshl_add_u64 v[24:25], v[64:65], 0, s[18:19]
	v_cvt_pk_bf16_f32 v26, v36, s0
	global_store_short v[24:25], v26, off
	v_lshl_add_u64 v[24:25], v[24:25], 0, s[8:9]
	v_cvt_pk_bf16_f32 v26, v37, s0
	global_store_short v[24:25], v26, off
	v_lshl_add_u64 v[24:25], v[24:25], 0, s[8:9]
	v_cvt_pk_bf16_f32 v26, v38, s0
	global_store_short v[24:25], v26, off
	v_lshl_add_u64 v[24:25], v[24:25], 0, s[8:9]
	v_cvt_pk_bf16_f32 v26, v39, s0
	global_store_short v[24:25], v26, off
	v_lshl_add_u64 v[24:25], v[24:25], 0, s[8:9]
	v_cvt_pk_bf16_f32 v26, v28, s0
	global_store_short v[24:25], v26, off
	v_lshl_add_u64 v[24:25], v[24:25], 0, s[8:9]
	v_cvt_pk_bf16_f32 v26, v29, s0
	global_store_short v[24:25], v26, off
	v_lshl_add_u64 v[24:25], v[24:25], 0, s[8:9]
	v_cvt_pk_bf16_f32 v26, v30, s0
	global_store_short v[24:25], v26, off
	v_lshl_add_u64 v[24:25], v[24:25], 0, s[8:9]
	v_cvt_pk_bf16_f32 v26, v31, s0
	global_store_short v[24:25], v26, off
	v_lshl_add_u64 v[24:25], v[24:25], 0, s[8:9]
	s_mov_b64 s[18:19], 0x8020
	v_lshl_add_u64 v[24:25], v[64:65], 0, s[18:19]
	v_cvt_pk_bf16_f32 v20, v20, s0
	global_store_short v[24:25], v20, off
	v_lshl_add_u64 v[24:25], v[24:25], 0, s[8:9]
	v_cvt_pk_bf16_f32 v20, v21, s0
	global_store_short v[24:25], v20, off
	v_lshl_add_u64 v[20:21], v[24:25], 0, s[8:9]
	v_cvt_pk_bf16_f32 v22, v22, s0
	global_store_short v[20:21], v22, off
	v_lshl_add_u64 v[20:21], v[20:21], 0, s[8:9]
	v_cvt_pk_bf16_f32 v22, v23, s0
	global_store_short v[20:21], v22, off
	v_lshl_add_u64 v[20:21], v[20:21], 0, s[8:9]
	v_cvt_pk_bf16_f32 v16, v16, s0
	global_store_short v[20:21], v16, off
	v_lshl_add_u64 v[20:21], v[20:21], 0, s[8:9]
	v_cvt_pk_bf16_f32 v16, v17, s0
	global_store_short v[20:21], v16, off
	v_lshl_add_u64 v[16:17], v[20:21], 0, s[8:9]
	v_cvt_pk_bf16_f32 v18, v18, s0
	global_store_short v[16:17], v18, off
	v_lshl_add_u64 v[16:17], v[16:17], 0, s[8:9]
	v_cvt_pk_bf16_f32 v18, v19, s0
	global_store_short v[16:17], v18, off
	v_lshl_add_u64 v[16:17], v[16:17], 0, s[8:9]
	s_mov_b64 s[18:19], 0x8040
	v_lshl_add_u64 v[16:17], v[64:65], 0, s[18:19]
	v_cvt_pk_bf16_f32 v12, v12, s0
	global_store_short v[16:17], v12, off
	v_lshl_add_u64 v[16:17], v[16:17], 0, s[8:9]
	v_cvt_pk_bf16_f32 v12, v13, s0
	global_store_short v[16:17], v12, off
	v_lshl_add_u64 v[12:13], v[16:17], 0, s[8:9]
	v_cvt_pk_bf16_f32 v14, v14, s0
	global_store_short v[12:13], v14, off
	v_lshl_add_u64 v[12:13], v[12:13], 0, s[8:9]
	v_cvt_pk_bf16_f32 v14, v15, s0
	global_store_short v[12:13], v14, off
	v_lshl_add_u64 v[12:13], v[12:13], 0, s[8:9]
	v_cvt_pk_bf16_f32 v8, v8, s0
	global_store_short v[12:13], v8, off
	v_lshl_add_u64 v[12:13], v[12:13], 0, s[8:9]
	v_cvt_pk_bf16_f32 v8, v9, s0
	global_store_short v[12:13], v8, off
	v_lshl_add_u64 v[8:9], v[12:13], 0, s[8:9]
	v_cvt_pk_bf16_f32 v10, v10, s0
	global_store_short v[8:9], v10, off
	v_lshl_add_u64 v[8:9], v[8:9], 0, s[8:9]
	v_cvt_pk_bf16_f32 v10, v11, s0
	global_store_short v[8:9], v10, off
	v_lshl_add_u64 v[8:9], v[8:9], 0, s[8:9]
	s_mov_b64 s[18:19], 0x8060
	v_lshl_add_u64 v[8:9], v[64:65], 0, s[18:19]
	v_cvt_pk_bf16_f32 v4, v4, s0
	global_store_short v[8:9], v4, off
	v_lshl_add_u64 v[8:9], v[8:9], 0, s[8:9]
	v_cvt_pk_bf16_f32 v4, v5, s0
	global_store_short v[8:9], v4, off
	v_lshl_add_u64 v[4:5], v[8:9], 0, s[8:9]
	v_cvt_pk_bf16_f32 v6, v6, s0
	global_store_short v[4:5], v6, off
	v_lshl_add_u64 v[4:5], v[4:5], 0, s[8:9]
	v_cvt_pk_bf16_f32 v6, v7, s0
	global_store_short v[4:5], v6, off
	v_lshl_add_u64 v[4:5], v[4:5], 0, s[8:9]
	v_cvt_pk_bf16_f32 v0, v0, s0
	global_store_short v[4:5], v0, off
	v_lshl_add_u64 v[4:5], v[4:5], 0, s[8:9]
	v_cvt_pk_bf16_f32 v0, v1, s0
	global_store_short v[4:5], v0, off
	v_lshl_add_u64 v[0:1], v[4:5], 0, s[8:9]
	v_cvt_pk_bf16_f32 v2, v2, s0
	global_store_short v[0:1], v2, off
	v_lshl_add_u64 v[0:1], v[0:1], 0, s[8:9]
	v_cvt_pk_bf16_f32 v2, v3, s0
	global_store_short v[0:1], v2, off
	v_lshl_add_u64 v[0:1], v[0:1], 0, s[8:9]
	s_andn2_b64 vcc, exec, s[0:1]
	s_mov_b64 s[0:1], -1
	s_cbranch_vccnz .LBB0_459
	s_andn2_b64 vcc, exec, s[4:5]
	s_cbranch_vccnz .LBB0_458
	s_barrier
	s_branch .LBB0_458
